# FFN-up K-loops alternate the K sweep direction per tile (even ascending, odd descending) so re-read A rows are L2-resident
# speedup vs baseline: 1.0067x; 1.0027x over previous
.LBB0_130:
	s_ashr_i32 s13, s12, 31
	v_cmp_lt_i64_e32 vcc, s[14:15], v[140:141]
	s_lshl_b64 s[14:15], s[12:13], 19
	s_add_u32 s14, s39, s14
	s_addc_u32 s15, s40, s15
	s_bitcmp1_b32 s50, 0
	s_cselect_b32 s88, 0x780, 0
	s_add_u32 s14, s14, s88
	s_addc_u32 s15, s15, 0
	s_and_b64 s[16:17], vcc, exec
	s_cselect_b32 s13, s15, s21
	s_cselect_b32 s53, s14, s20
	s_ashr_i32 s11, s10, 31
	s_lshl_b64 s[16:17], s[10:11], 19
	s_add_u32 s16, s33, s16
	s_addc_u32 s17, s34, s17
	s_bitcmp1_b32 s50, 0
	s_cselect_b32 s88, 0x780, 0
	s_add_u32 s16, s16, s88
	s_addc_u32 s17, s17, 0
	s_and_b64 s[28:29], vcc, exec
	s_cselect_b32 s11, s17, s27
	s_cselect_b32 s54, s16, s26
	s_movk_i32 s98, 0x80
	s_bitcmp1_b32 s51, 0
	s_cselect_b32 s98, 0xffffff80, s98
	s_cselect_b32 s99, -1, 0
	s_add_u32 s20, s20, 0x40000
	s_addc_u32 s21, s21, 0
	s_add_u32 s20, s20, s98
	s_addc_u32 s21, s21, s99
	s_lshl_b32 s88, s98, 1
	s_add_u32 s55, s26, s88
	s_addc_u32 s56, s27, s99
	s_mov_b32 s57, -2
	s_setprio 0
	s_cmpk_lt_u32 s37, 0x100
	s_cbranch_scc1 .Lg131_noy
	s_setprio 1
	s_barrier
.Lg131_noy:
	ds_read_b128 v[152:155], v149
	ds_read_b128 v[156:159], v149 offset:1024
	ds_read_b128 v[160:163], v149 offset:2048
	ds_read_b128 v[164:167], v149 offset:3072
	s_add_u32 s26, s20, 0xfffc0000
	s_addc_u32 s27, s21, -1
	s_add_u32 s26, s26, s98
	s_addc_u32 s27, s27, s99
	s_sub_i32 s89, 0, s98
	s_not_b32 s90, s99
	s_cmp_eq_u32 s57, 12
	s_cselect_b32 s29, s13, s27
	s_cselect_b32 s28, s53, s26
	s_cselect_b32 s27, s11, s56
	s_cselect_b32 s26, s54, s55
	s_cselect_b32 s100, s89, s98
	s_cselect_b32 s101, s90, s99
	s_add_i32 m0, s19, 0xc000
	ds_read_b128 v[168:171], v150
	ds_read_b128 v[172:175], v150 offset:1024
	ds_read_b128 v[176:179], v150 offset:2048
	ds_read_b128 v[180:183], v150 offset:3072
	ds_read_b128 v[184:187], v150 offset:4096
	ds_read_b128 v[188:191], v150 offset:5120
	ds_read_b128 v[192:195], v150 offset:6144
	ds_read_b128 v[196:199], v150 offset:7168
	global_load_lds_dwordx4 v136, s[20:21]
	s_add_i32 m0, s19, 0xe000
	s_nop 0
	global_load_lds_dwordx4 v138, s[20:21]
	s_waitcnt lgkmcnt(8)
	s_barrier
	s_waitcnt lgkmcnt(0)
	s_waitcnt lgkmcnt(0)
	v_mfma_f32_16x16x32_bf16 v[124:127], v[152:155], v[168:171], 0
	v_mfma_f32_16x16x32_bf16 v[120:123], v[160:163], v[168:171], 0
	v_mfma_f32_16x16x32_bf16 v[108:111], v[152:155], v[176:179], 0
	v_mfma_f32_16x16x32_bf16 v[104:107], v[160:163], v[176:179], 0
	v_mfma_f32_16x16x32_bf16 v[92:95], v[152:155], v[184:187], 0
	v_mfma_f32_16x16x32_bf16 v[88:91], v[160:163], v[184:187], 0
	v_mfma_f32_16x16x32_bf16 v[76:79], v[152:155], v[192:195], 0
	v_mfma_f32_16x16x32_bf16 v[72:75], v[160:163], v[192:195], 0
	v_mfma_f32_16x16x32_bf16 v[124:127], v[156:159], v[172:175], v[124:127]
	v_mfma_f32_16x16x32_bf16 v[120:123], v[164:167], v[172:175], v[120:123]
	v_mfma_f32_16x16x32_bf16 v[108:111], v[156:159], v[180:183], v[108:111]
	v_mfma_f32_16x16x32_bf16 v[104:107], v[164:167], v[180:183], v[104:107]
	v_mfma_f32_16x16x32_bf16 v[92:95], v[156:159], v[188:191], v[92:95]
	v_mfma_f32_16x16x32_bf16 v[88:91], v[164:167], v[188:191], v[88:91]
	v_mfma_f32_16x16x32_bf16 v[76:79], v[156:159], v[196:199], v[76:79]
	v_mfma_f32_16x16x32_bf16 v[72:75], v[164:167], v[196:199], v[72:75]
	s_barrier
	s_add_i32 s58, s47, s38
	s_add_u32 s80, s26, s100
	s_addc_u32 s81, s27, s101
	s_mov_b32 m0, s58
	ds_read_b128 v[200:203], v151
	ds_read_b128 v[204:207], v151 offset:1024
	ds_read_b128 v[208:211], v151 offset:2048
	ds_read_b128 v[212:215], v151 offset:3072
	global_load_lds_dwordx4 v132, s[26:27]
	s_add_i32 m0, s58, 0x2000
	s_nop 0
	global_load_lds_dwordx4 v128, s[26:27]
	s_waitcnt vmcnt(10)
	s_barrier
	s_waitcnt lgkmcnt(0)
	s_waitcnt lgkmcnt(0)
	v_mfma_f32_16x16x32_bf16 v[116:119], v[200:203], v[168:171], 0
	v_mfma_f32_16x16x32_bf16 v[112:115], v[208:211], v[168:171], 0
	v_mfma_f32_16x16x32_bf16 v[100:103], v[200:203], v[176:179], 0
	v_mfma_f32_16x16x32_bf16 v[96:99], v[208:211], v[176:179], 0
	v_mfma_f32_16x16x32_bf16 v[84:87], v[200:203], v[184:187], 0
	v_mfma_f32_16x16x32_bf16 v[80:83], v[208:211], v[184:187], 0
	v_mfma_f32_16x16x32_bf16 v[68:71], v[200:203], v[192:195], 0
	v_mfma_f32_16x16x32_bf16 v[64:67], v[208:211], v[192:195], 0
	v_mfma_f32_16x16x32_bf16 v[116:119], v[204:207], v[172:175], v[116:119]
	v_mfma_f32_16x16x32_bf16 v[112:115], v[212:215], v[172:175], v[112:115]
	v_mfma_f32_16x16x32_bf16 v[100:103], v[204:207], v[180:183], v[100:103]
	v_mfma_f32_16x16x32_bf16 v[96:99], v[212:215], v[180:183], v[96:99]
	v_mfma_f32_16x16x32_bf16 v[84:87], v[204:207], v[188:191], v[84:87]
	v_mfma_f32_16x16x32_bf16 v[80:83], v[212:215], v[188:191], v[80:83]
	v_mfma_f32_16x16x32_bf16 v[68:71], v[204:207], v[196:199], v[68:71]
	v_mfma_f32_16x16x32_bf16 v[64:67], v[212:215], v[196:199], v[64:67]
	s_mov_b32 m0, s19
	s_add_u32 s82, s28, s100
	s_addc_u32 s83, s29, s101
	s_barrier
	ds_read_b128 v[168:171], v150 offset:16384
	ds_read_b128 v[172:175], v150 offset:17408
	ds_read_b128 v[176:179], v150 offset:18432
	ds_read_b128 v[180:183], v150 offset:19456
	ds_read_b128 v[184:187], v150 offset:20480
	ds_read_b128 v[188:191], v150 offset:21504
	ds_read_b128 v[192:195], v150 offset:22528
	ds_read_b128 v[196:199], v150 offset:23552
	global_load_lds_dwordx4 v134, s[28:29]
	s_mov_b32 m0, s42
	s_nop 0
	global_load_lds_dwordx4 v130, s[28:29]
	s_barrier
	s_waitcnt lgkmcnt(0)
	s_waitcnt lgkmcnt(0)
	v_mfma_f32_16x16x32_bf16 v[60:63], v[152:155], v[168:171], 0
	v_mfma_f32_16x16x32_bf16 v[56:59], v[160:163], v[168:171], 0
	v_mfma_f32_16x16x32_bf16 v[44:47], v[152:155], v[176:179], 0
	v_mfma_f32_16x16x32_bf16 v[40:43], v[160:163], v[176:179], 0
	v_mfma_f32_16x16x32_bf16 v[28:31], v[152:155], v[184:187], 0
	v_mfma_f32_16x16x32_bf16 v[24:27], v[160:163], v[184:187], 0
	v_mfma_f32_16x16x32_bf16 v[12:15], v[152:155], v[192:195], 0
	v_mfma_f32_16x16x32_bf16 v[8:11], v[160:163], v[192:195], 0
	v_mfma_f32_16x16x32_bf16 v[60:63], v[156:159], v[172:175], v[60:63]
	v_mfma_f32_16x16x32_bf16 v[56:59], v[164:167], v[172:175], v[56:59]
	v_mfma_f32_16x16x32_bf16 v[44:47], v[156:159], v[180:183], v[44:47]
	v_mfma_f32_16x16x32_bf16 v[40:43], v[164:167], v[180:183], v[40:43]
	v_mfma_f32_16x16x32_bf16 v[28:31], v[156:159], v[188:191], v[28:31]
	v_mfma_f32_16x16x32_bf16 v[24:27], v[164:167], v[188:191], v[24:27]
	v_mfma_f32_16x16x32_bf16 v[12:15], v[156:159], v[196:199], v[12:15]
	v_mfma_f32_16x16x32_bf16 v[8:11], v[164:167], v[196:199], v[8:11]
	s_barrier
	s_add_u32 s58, s26, 0x40000
	s_addc_u32 s59, s27, 0
	s_add_i32 s60, s48, s38
	s_mov_b32 m0, s60
	s_nop 0
	global_load_lds_dwordx4 v132, s[58:59]
	s_add_i32 m0, s60, 0x2000
	s_nop 0
	global_load_lds_dwordx4 v128, s[58:59]
	s_waitcnt vmcnt(8)
	s_barrier
	v_mfma_f32_16x16x32_bf16 v[52:55], v[200:203], v[168:171], 0
	v_mfma_f32_16x16x32_bf16 v[48:51], v[208:211], v[168:171], 0
	v_mfma_f32_16x16x32_bf16 v[36:39], v[200:203], v[176:179], 0
	v_mfma_f32_16x16x32_bf16 v[32:35], v[208:211], v[176:179], 0
	v_mfma_f32_16x16x32_bf16 v[20:23], v[200:203], v[184:187], 0
	v_mfma_f32_16x16x32_bf16 v[16:19], v[208:211], v[184:187], 0
	v_mfma_f32_16x16x32_bf16 v[4:7], v[200:203], v[192:195], 0
	v_mfma_f32_16x16x32_bf16 v[0:3], v[208:211], v[192:195], 0
	v_mfma_f32_16x16x32_bf16 v[52:55], v[204:207], v[172:175], v[52:55]
	v_mfma_f32_16x16x32_bf16 v[48:51], v[212:215], v[172:175], v[48:51]
	v_mfma_f32_16x16x32_bf16 v[36:39], v[204:207], v[180:183], v[36:39]
	v_mfma_f32_16x16x32_bf16 v[32:35], v[212:215], v[180:183], v[32:35]
	v_mfma_f32_16x16x32_bf16 v[20:23], v[204:207], v[188:191], v[20:23]
	v_mfma_f32_16x16x32_bf16 v[16:19], v[212:215], v[188:191], v[16:19]
	v_mfma_f32_16x16x32_bf16 v[4:7], v[204:207], v[196:199], v[4:7]
	v_mfma_f32_16x16x32_bf16 v[0:3], v[212:215], v[196:199], v[0:3]
	s_add_i32 s58, 0, 0x18000
	v_add_u32_e32 v164, s58, v145
	s_barrier
	s_branch .Lg131_mid
.LBB0_131:
	ds_read_b128 v[152:155], v149
	ds_read_b128 v[156:159], v149 offset:1024
	ds_read_b128 v[160:163], v149 offset:2048
	ds_read_b128 v[164:167], v149 offset:3072
	s_add_u32 s26, s20, 0xfffc0000
	s_addc_u32 s27, s21, -1
	s_add_u32 s26, s26, s98
	s_addc_u32 s27, s27, s99
	s_sub_i32 s89, 0, s98
	s_not_b32 s90, s99
	s_cmp_eq_u32 s57, 12
	s_cselect_b32 s29, s13, s27
	s_cselect_b32 s28, s53, s26
	s_cselect_b32 s27, s11, s56
	s_cselect_b32 s26, s54, s55
	s_cselect_b32 s100, s89, s98
	s_cselect_b32 s101, s90, s99
	s_add_i32 m0, s19, 0xc000
	ds_read_b128 v[168:171], v150
	ds_read_b128 v[172:175], v150 offset:1024
	ds_read_b128 v[176:179], v150 offset:2048
	ds_read_b128 v[180:183], v150 offset:3072
	ds_read_b128 v[184:187], v150 offset:4096
	ds_read_b128 v[188:191], v150 offset:5120
	ds_read_b128 v[192:195], v150 offset:6144
	ds_read_b128 v[196:199], v150 offset:7168
	global_load_lds_dwordx4 v136, s[20:21]
	s_add_i32 m0, s19, 0xe000
	s_nop 0
	global_load_lds_dwordx4 v138, s[20:21]
	s_waitcnt lgkmcnt(8)
	s_barrier
	s_waitcnt lgkmcnt(0)
	s_waitcnt lgkmcnt(0)
	v_mfma_f32_16x16x32_bf16 v[124:127], v[152:155], v[168:171], v[124:127]
	v_mfma_f32_16x16x32_bf16 v[120:123], v[160:163], v[168:171], v[120:123]
	v_mfma_f32_16x16x32_bf16 v[108:111], v[152:155], v[176:179], v[108:111]
	v_mfma_f32_16x16x32_bf16 v[104:107], v[160:163], v[176:179], v[104:107]
	v_mfma_f32_16x16x32_bf16 v[92:95], v[152:155], v[184:187], v[92:95]
	v_mfma_f32_16x16x32_bf16 v[88:91], v[160:163], v[184:187], v[88:91]
	v_mfma_f32_16x16x32_bf16 v[76:79], v[152:155], v[192:195], v[76:79]
	v_mfma_f32_16x16x32_bf16 v[72:75], v[160:163], v[192:195], v[72:75]
	v_mfma_f32_16x16x32_bf16 v[124:127], v[156:159], v[172:175], v[124:127]
	v_mfma_f32_16x16x32_bf16 v[120:123], v[164:167], v[172:175], v[120:123]
	v_mfma_f32_16x16x32_bf16 v[108:111], v[156:159], v[180:183], v[108:111]
	v_mfma_f32_16x16x32_bf16 v[104:107], v[164:167], v[180:183], v[104:107]
	v_mfma_f32_16x16x32_bf16 v[92:95], v[156:159], v[188:191], v[92:95]
	v_mfma_f32_16x16x32_bf16 v[88:91], v[164:167], v[188:191], v[88:91]
	v_mfma_f32_16x16x32_bf16 v[76:79], v[156:159], v[196:199], v[76:79]
	v_mfma_f32_16x16x32_bf16 v[72:75], v[164:167], v[196:199], v[72:75]
	s_barrier
	s_add_i32 s58, s47, s38
	s_add_u32 s80, s26, s100
	s_addc_u32 s81, s27, s101
	s_mov_b32 m0, s58
	ds_read_b128 v[200:203], v151
	ds_read_b128 v[204:207], v151 offset:1024
	ds_read_b128 v[208:211], v151 offset:2048
	ds_read_b128 v[212:215], v151 offset:3072
	global_load_lds_dwordx4 v132, s[26:27]
	s_add_i32 m0, s58, 0x2000
	s_nop 0
	global_load_lds_dwordx4 v128, s[26:27]
	s_waitcnt vmcnt(10)
	s_barrier
	s_waitcnt lgkmcnt(0)
	s_waitcnt lgkmcnt(0)
	v_mfma_f32_16x16x32_bf16 v[116:119], v[200:203], v[168:171], v[116:119]
	v_mfma_f32_16x16x32_bf16 v[112:115], v[208:211], v[168:171], v[112:115]
	v_mfma_f32_16x16x32_bf16 v[100:103], v[200:203], v[176:179], v[100:103]
	v_mfma_f32_16x16x32_bf16 v[96:99], v[208:211], v[176:179], v[96:99]
	v_mfma_f32_16x16x32_bf16 v[84:87], v[200:203], v[184:187], v[84:87]
	v_mfma_f32_16x16x32_bf16 v[80:83], v[208:211], v[184:187], v[80:83]
	v_mfma_f32_16x16x32_bf16 v[68:71], v[200:203], v[192:195], v[68:71]
	v_mfma_f32_16x16x32_bf16 v[64:67], v[208:211], v[192:195], v[64:67]
	v_mfma_f32_16x16x32_bf16 v[116:119], v[204:207], v[172:175], v[116:119]
	v_mfma_f32_16x16x32_bf16 v[112:115], v[212:215], v[172:175], v[112:115]
	v_mfma_f32_16x16x32_bf16 v[100:103], v[204:207], v[180:183], v[100:103]
	v_mfma_f32_16x16x32_bf16 v[96:99], v[212:215], v[180:183], v[96:99]
	v_mfma_f32_16x16x32_bf16 v[84:87], v[204:207], v[188:191], v[84:87]
	v_mfma_f32_16x16x32_bf16 v[80:83], v[212:215], v[188:191], v[80:83]
	v_mfma_f32_16x16x32_bf16 v[68:71], v[204:207], v[196:199], v[68:71]
	v_mfma_f32_16x16x32_bf16 v[64:67], v[212:215], v[196:199], v[64:67]
	s_mov_b32 m0, s19
	s_add_u32 s82, s28, s100
	s_addc_u32 s83, s29, s101
	s_barrier
	ds_read_b128 v[168:171], v150 offset:16384
	ds_read_b128 v[172:175], v150 offset:17408
	ds_read_b128 v[176:179], v150 offset:18432
	ds_read_b128 v[180:183], v150 offset:19456
	ds_read_b128 v[184:187], v150 offset:20480
	ds_read_b128 v[188:191], v150 offset:21504
	ds_read_b128 v[192:195], v150 offset:22528
	ds_read_b128 v[196:199], v150 offset:23552
	global_load_lds_dwordx4 v134, s[28:29]
	s_mov_b32 m0, s42
	s_nop 0
	global_load_lds_dwordx4 v130, s[28:29]
	s_barrier
	s_waitcnt lgkmcnt(0)
	s_waitcnt lgkmcnt(0)
	v_mfma_f32_16x16x32_bf16 v[60:63], v[152:155], v[168:171], v[60:63]
	v_mfma_f32_16x16x32_bf16 v[56:59], v[160:163], v[168:171], v[56:59]
	v_mfma_f32_16x16x32_bf16 v[44:47], v[152:155], v[176:179], v[44:47]
	v_mfma_f32_16x16x32_bf16 v[40:43], v[160:163], v[176:179], v[40:43]
	v_mfma_f32_16x16x32_bf16 v[28:31], v[152:155], v[184:187], v[28:31]
	v_mfma_f32_16x16x32_bf16 v[24:27], v[160:163], v[184:187], v[24:27]
	v_mfma_f32_16x16x32_bf16 v[12:15], v[152:155], v[192:195], v[12:15]
	v_mfma_f32_16x16x32_bf16 v[8:11], v[160:163], v[192:195], v[8:11]
	v_mfma_f32_16x16x32_bf16 v[60:63], v[156:159], v[172:175], v[60:63]
	v_mfma_f32_16x16x32_bf16 v[56:59], v[164:167], v[172:175], v[56:59]
	v_mfma_f32_16x16x32_bf16 v[44:47], v[156:159], v[180:183], v[44:47]
	v_mfma_f32_16x16x32_bf16 v[40:43], v[164:167], v[180:183], v[40:43]
	v_mfma_f32_16x16x32_bf16 v[28:31], v[156:159], v[188:191], v[28:31]
	v_mfma_f32_16x16x32_bf16 v[24:27], v[164:167], v[188:191], v[24:27]
	v_mfma_f32_16x16x32_bf16 v[12:15], v[156:159], v[196:199], v[12:15]
	v_mfma_f32_16x16x32_bf16 v[8:11], v[164:167], v[196:199], v[8:11]
	s_barrier
	s_add_u32 s58, s26, 0x40000
	s_addc_u32 s59, s27, 0
	s_add_i32 s60, s48, s38
	s_mov_b32 m0, s60
	s_nop 0
	global_load_lds_dwordx4 v132, s[58:59]
	s_add_i32 m0, s60, 0x2000
	s_nop 0
	global_load_lds_dwordx4 v128, s[58:59]
	s_waitcnt vmcnt(8)
	s_barrier
	v_mfma_f32_16x16x32_bf16 v[52:55], v[200:203], v[168:171], v[52:55]
	v_mfma_f32_16x16x32_bf16 v[48:51], v[208:211], v[168:171], v[48:51]
	v_mfma_f32_16x16x32_bf16 v[36:39], v[200:203], v[176:179], v[36:39]
	v_mfma_f32_16x16x32_bf16 v[32:35], v[208:211], v[176:179], v[32:35]
	v_mfma_f32_16x16x32_bf16 v[20:23], v[200:203], v[184:187], v[20:23]
	v_mfma_f32_16x16x32_bf16 v[16:19], v[208:211], v[184:187], v[16:19]
	v_mfma_f32_16x16x32_bf16 v[4:7], v[200:203], v[192:195], v[4:7]
	v_mfma_f32_16x16x32_bf16 v[0:3], v[208:211], v[192:195], v[0:3]
	v_mfma_f32_16x16x32_bf16 v[52:55], v[204:207], v[172:175], v[52:55]
	v_mfma_f32_16x16x32_bf16 v[48:51], v[212:215], v[172:175], v[48:51]
	v_mfma_f32_16x16x32_bf16 v[36:39], v[204:207], v[180:183], v[36:39]
	v_mfma_f32_16x16x32_bf16 v[32:35], v[212:215], v[180:183], v[32:35]
	v_mfma_f32_16x16x32_bf16 v[20:23], v[204:207], v[188:191], v[20:23]
	v_mfma_f32_16x16x32_bf16 v[16:19], v[212:215], v[188:191], v[16:19]
	v_mfma_f32_16x16x32_bf16 v[4:7], v[204:207], v[196:199], v[4:7]
	v_mfma_f32_16x16x32_bf16 v[0:3], v[212:215], v[196:199], v[0:3]
	s_add_i32 s58, 0, 0x18000
	v_add_u32_e32 v164, s58, v145
	s_barrier
.Lg131_mid:
	ds_read_b128 v[152:155], v164
	ds_read_b128 v[156:159], v164 offset:1024
	ds_read_b128 v[160:163], v164 offset:2048
	ds_read_b128 v[164:167], v164 offset:3072
	s_add_u32 s28, s28, 0x40000
	s_addc_u32 s29, s29, 0
	s_mov_b32 m0, s43
	ds_read_b128 v[168:171], v150 offset:32768
	ds_read_b128 v[172:175], v150 offset:33792
	ds_read_b128 v[176:179], v150 offset:34816
	ds_read_b128 v[180:183], v150 offset:35840
	ds_read_b128 v[184:187], v150 offset:36864
	ds_read_b128 v[188:191], v150 offset:37888
	ds_read_b128 v[192:195], v150 offset:38912
	ds_read_b128 v[196:199], v150 offset:39936
	global_load_lds_dwordx4 v134, s[28:29]
	s_mov_b32 m0, s44
	s_nop 0
	global_load_lds_dwordx4 v130, s[28:29]
	s_waitcnt lgkmcnt(8)
	s_barrier
	s_waitcnt lgkmcnt(0)
	s_waitcnt lgkmcnt(0)
	v_mfma_f32_16x16x32_bf16 v[124:127], v[152:155], v[168:171], v[124:127]
	v_mfma_f32_16x16x32_bf16 v[120:123], v[160:163], v[168:171], v[120:123]
	v_mfma_f32_16x16x32_bf16 v[108:111], v[152:155], v[176:179], v[108:111]
	v_mfma_f32_16x16x32_bf16 v[104:107], v[160:163], v[176:179], v[104:107]
	v_mfma_f32_16x16x32_bf16 v[92:95], v[152:155], v[184:187], v[92:95]
	v_mfma_f32_16x16x32_bf16 v[88:91], v[160:163], v[184:187], v[88:91]
	v_mfma_f32_16x16x32_bf16 v[76:79], v[152:155], v[192:195], v[76:79]
	v_mfma_f32_16x16x32_bf16 v[72:75], v[160:163], v[192:195], v[72:75]
	v_mfma_f32_16x16x32_bf16 v[124:127], v[156:159], v[172:175], v[124:127]
	v_mfma_f32_16x16x32_bf16 v[120:123], v[164:167], v[172:175], v[120:123]
	v_mfma_f32_16x16x32_bf16 v[108:111], v[156:159], v[180:183], v[108:111]
	v_mfma_f32_16x16x32_bf16 v[104:107], v[164:167], v[180:183], v[104:107]
	v_mfma_f32_16x16x32_bf16 v[92:95], v[156:159], v[188:191], v[92:95]
	v_mfma_f32_16x16x32_bf16 v[88:91], v[164:167], v[188:191], v[88:91]
	v_mfma_f32_16x16x32_bf16 v[76:79], v[156:159], v[196:199], v[76:79]
	v_mfma_f32_16x16x32_bf16 v[72:75], v[164:167], v[196:199], v[72:75]
	s_barrier
	s_add_i32 s28, 0, 0x1c000
	s_add_i32 s29, s58, s38
	v_add_u32_e32 v212, s28, v145
	s_mov_b32 m0, s29
	ds_read_b128 v[200:203], v212
	ds_read_b128 v[204:207], v212 offset:1024
	ds_read_b128 v[208:211], v212 offset:2048
	ds_read_b128 v[212:215], v212 offset:3072
	global_load_lds_dwordx4 v132, s[80:81]
	s_add_i32 m0, s29, 0x2000
	s_nop 0
	global_load_lds_dwordx4 v128, s[80:81]
	s_waitcnt vmcnt(10)
	s_barrier
	s_waitcnt lgkmcnt(0)
	s_waitcnt lgkmcnt(0)
	v_mfma_f32_16x16x32_bf16 v[116:119], v[200:203], v[168:171], v[116:119]
	v_mfma_f32_16x16x32_bf16 v[112:115], v[208:211], v[168:171], v[112:115]
	v_mfma_f32_16x16x32_bf16 v[100:103], v[200:203], v[176:179], v[100:103]
	v_mfma_f32_16x16x32_bf16 v[96:99], v[208:211], v[176:179], v[96:99]
	v_mfma_f32_16x16x32_bf16 v[84:87], v[200:203], v[184:187], v[84:87]
	v_mfma_f32_16x16x32_bf16 v[80:83], v[208:211], v[184:187], v[80:83]
	v_mfma_f32_16x16x32_bf16 v[68:71], v[200:203], v[192:195], v[68:71]
	v_mfma_f32_16x16x32_bf16 v[64:67], v[208:211], v[192:195], v[64:67]
	v_mfma_f32_16x16x32_bf16 v[116:119], v[204:207], v[172:175], v[116:119]
	v_mfma_f32_16x16x32_bf16 v[112:115], v[212:215], v[172:175], v[112:115]
	v_mfma_f32_16x16x32_bf16 v[100:103], v[204:207], v[180:183], v[100:103]
	v_mfma_f32_16x16x32_bf16 v[96:99], v[212:215], v[180:183], v[96:99]
	v_mfma_f32_16x16x32_bf16 v[84:87], v[204:207], v[188:191], v[84:87]
	v_mfma_f32_16x16x32_bf16 v[80:83], v[212:215], v[188:191], v[80:83]
	v_mfma_f32_16x16x32_bf16 v[68:71], v[204:207], v[196:199], v[68:71]
	v_mfma_f32_16x16x32_bf16 v[64:67], v[212:215], v[196:199], v[64:67]
	s_mov_b32 m0, s45
	s_barrier
	ds_read_b128 v[168:171], v150 offset:49152
	ds_read_b128 v[172:175], v150 offset:50176
	ds_read_b128 v[176:179], v150 offset:51200
	ds_read_b128 v[180:183], v150 offset:52224
	ds_read_b128 v[184:187], v150 offset:53248
	ds_read_b128 v[188:191], v150 offset:54272
	ds_read_b128 v[192:195], v150 offset:55296
	ds_read_b128 v[196:199], v150 offset:56320
	global_load_lds_dwordx4 v134, s[82:83]
	s_mov_b32 m0, s46
	s_nop 0
	global_load_lds_dwordx4 v130, s[82:83]
	s_barrier
	s_waitcnt lgkmcnt(0)
	s_waitcnt lgkmcnt(0)
	v_mfma_f32_16x16x32_bf16 v[60:63], v[152:155], v[168:171], v[60:63]
	v_mfma_f32_16x16x32_bf16 v[56:59], v[160:163], v[168:171], v[56:59]
	v_mfma_f32_16x16x32_bf16 v[44:47], v[152:155], v[176:179], v[44:47]
	v_mfma_f32_16x16x32_bf16 v[40:43], v[160:163], v[176:179], v[40:43]
	v_mfma_f32_16x16x32_bf16 v[28:31], v[152:155], v[184:187], v[28:31]
	v_mfma_f32_16x16x32_bf16 v[24:27], v[160:163], v[184:187], v[24:27]
	v_mfma_f32_16x16x32_bf16 v[12:15], v[152:155], v[192:195], v[12:15]
	v_mfma_f32_16x16x32_bf16 v[8:11], v[160:163], v[192:195], v[8:11]
	v_mfma_f32_16x16x32_bf16 v[60:63], v[156:159], v[172:175], v[60:63]
	v_mfma_f32_16x16x32_bf16 v[56:59], v[164:167], v[172:175], v[56:59]
	v_mfma_f32_16x16x32_bf16 v[44:47], v[156:159], v[180:183], v[44:47]
	v_mfma_f32_16x16x32_bf16 v[40:43], v[164:167], v[180:183], v[40:43]
	v_mfma_f32_16x16x32_bf16 v[28:31], v[156:159], v[188:191], v[28:31]
	v_mfma_f32_16x16x32_bf16 v[24:27], v[164:167], v[188:191], v[24:27]
	v_mfma_f32_16x16x32_bf16 v[12:15], v[156:159], v[196:199], v[12:15]
	v_mfma_f32_16x16x32_bf16 v[8:11], v[164:167], v[196:199], v[8:11]
	s_barrier
	s_add_u32 s26, s26, 0x40000
	s_addc_u32 s27, s27, 0
	s_add_u32 s26, s26, s100
	s_addc_u32 s27, s27, s101
	s_add_i32 s28, s28, s38
	s_mov_b32 m0, s28
	s_nop 0
	global_load_lds_dwordx4 v132, s[26:27]
	s_add_i32 m0, s28, 0x2000
	s_nop 0
	global_load_lds_dwordx4 v128, s[26:27]
	s_waitcnt vmcnt(8)
	s_barrier
	v_mfma_f32_16x16x32_bf16 v[52:55], v[200:203], v[168:171], v[52:55]
	v_mfma_f32_16x16x32_bf16 v[48:51], v[208:211], v[168:171], v[48:51]
	v_mfma_f32_16x16x32_bf16 v[36:39], v[200:203], v[176:179], v[36:39]
	v_mfma_f32_16x16x32_bf16 v[32:35], v[208:211], v[176:179], v[32:35]
	v_mfma_f32_16x16x32_bf16 v[20:23], v[200:203], v[184:187], v[20:23]
	v_mfma_f32_16x16x32_bf16 v[16:19], v[208:211], v[184:187], v[16:19]
	v_mfma_f32_16x16x32_bf16 v[4:7], v[200:203], v[192:195], v[4:7]
	v_mfma_f32_16x16x32_bf16 v[0:3], v[208:211], v[192:195], v[0:3]
	v_mfma_f32_16x16x32_bf16 v[52:55], v[204:207], v[172:175], v[52:55]
	v_mfma_f32_16x16x32_bf16 v[48:51], v[212:215], v[172:175], v[48:51]
	v_mfma_f32_16x16x32_bf16 v[36:39], v[204:207], v[180:183], v[36:39]
	v_mfma_f32_16x16x32_bf16 v[32:35], v[212:215], v[180:183], v[32:35]
	v_mfma_f32_16x16x32_bf16 v[20:23], v[204:207], v[188:191], v[20:23]
	v_mfma_f32_16x16x32_bf16 v[16:19], v[212:215], v[188:191], v[16:19]
	v_mfma_f32_16x16x32_bf16 v[4:7], v[204:207], v[196:199], v[4:7]
	v_mfma_f32_16x16x32_bf16 v[0:3], v[212:215], v[196:199], v[0:3]
	s_add_i32 s57, s57, 2
	s_lshl_b32 s88, s98, 1
	s_add_u32 s20, s20, s88
	s_addc_u32 s21, s21, s99
	s_add_u32 s55, s55, s88
	s_addc_u32 s56, s56, s99
	s_cmp_gt_u32 s57, 13
	s_barrier
	s_cbranch_scc0 .LBB0_131
	s_setprio 0
	s_cmpk_gt_u32 s37, 0xff
	s_cbranch_scc1 .Lg131_nox
	s_barrier
	s_setprio 1

.LBB0_892:
	s_ashr_i32 s13, s12, 31
	v_cmp_lt_i64_e32 vcc, s[14:15], v[140:141]
	s_lshl_b64 s[14:15], s[12:13], 19
	s_add_u32 s14, s37, s14
	s_addc_u32 s15, s38, s15
	s_bitcmp1_b32 s50, 0
	s_cselect_b32 s88, 0x780, 0
	s_add_u32 s14, s14, s88
	s_addc_u32 s15, s15, 0
	s_and_b64 s[16:17], vcc, exec
	s_cselect_b32 s13, s15, s21
	s_cselect_b32 s53, s14, s20
	s_ashr_i32 s11, s10, 31
	s_lshl_b64 s[16:17], s[10:11], 19
	s_add_u32 s16, s39, s16
	s_addc_u32 s17, s40, s17
	s_bitcmp1_b32 s50, 0
	s_cselect_b32 s88, 0x780, 0
	s_add_u32 s16, s16, s88
	s_addc_u32 s17, s17, 0
	s_and_b64 s[28:29], vcc, exec
	s_cselect_b32 s11, s17, s27
	s_cselect_b32 s54, s16, s26
	s_movk_i32 s98, 0x80
	s_bitcmp1_b32 s51, 0
	s_cselect_b32 s98, 0xffffff80, s98
	s_cselect_b32 s99, -1, 0
	s_add_u32 s20, s20, 0x40000
	s_addc_u32 s21, s21, 0
	s_add_u32 s20, s20, s98
	s_addc_u32 s21, s21, s99
	s_lshl_b32 s88, s98, 1
	s_add_u32 s55, s26, s88
	s_addc_u32 s56, s27, s99
	s_mov_b32 s57, -2
	s_setprio 0
	s_cmpk_lt_u32 s30, 0x100
	s_cbranch_scc1 .Lg893_noy
	s_setprio 1
	s_barrier
.Lg893_noy:
	ds_read_b128 v[152:155], v148
	ds_read_b128 v[156:159], v148 offset:1024
	ds_read_b128 v[160:163], v148 offset:2048
	ds_read_b128 v[164:167], v148 offset:3072
	s_add_u32 s26, s20, 0xfffc0000
	s_addc_u32 s27, s21, -1
	s_add_u32 s26, s26, s98
	s_addc_u32 s27, s27, s99
	s_sub_i32 s89, 0, s98
	s_not_b32 s90, s99
	s_cmp_eq_u32 s57, 12
	s_cselect_b32 s29, s13, s27
	s_cselect_b32 s28, s53, s26
	s_cselect_b32 s27, s11, s56
	s_cselect_b32 s26, s54, s55
	s_cselect_b32 s100, s89, s98
	s_cselect_b32 s101, s90, s99
	s_add_i32 m0, s19, 0xc000
	ds_read_b128 v[168:171], v149
	ds_read_b128 v[172:175], v149 offset:1024
	ds_read_b128 v[176:179], v149 offset:2048
	ds_read_b128 v[180:183], v149 offset:3072
	ds_read_b128 v[184:187], v149 offset:4096
	ds_read_b128 v[188:191], v149 offset:5120
	ds_read_b128 v[192:195], v149 offset:6144
	ds_read_b128 v[196:199], v149 offset:7168
	global_load_lds_dwordx4 v136, s[20:21]
	s_add_i32 m0, s19, 0xe000
	s_nop 0
	global_load_lds_dwordx4 v138, s[20:21]
	s_waitcnt lgkmcnt(8)
	s_barrier
	s_waitcnt lgkmcnt(0)
	s_waitcnt lgkmcnt(0)
	v_mfma_f32_16x16x32_bf16 v[124:127], v[152:155], v[168:171], 0
	v_mfma_f32_16x16x32_bf16 v[120:123], v[160:163], v[168:171], 0
	v_mfma_f32_16x16x32_bf16 v[108:111], v[152:155], v[176:179], 0
	v_mfma_f32_16x16x32_bf16 v[104:107], v[160:163], v[176:179], 0
	v_mfma_f32_16x16x32_bf16 v[92:95], v[152:155], v[184:187], 0
	v_mfma_f32_16x16x32_bf16 v[88:91], v[160:163], v[184:187], 0
	v_mfma_f32_16x16x32_bf16 v[76:79], v[152:155], v[192:195], 0
	v_mfma_f32_16x16x32_bf16 v[72:75], v[160:163], v[192:195], 0
	v_mfma_f32_16x16x32_bf16 v[124:127], v[156:159], v[172:175], v[124:127]
	v_mfma_f32_16x16x32_bf16 v[120:123], v[164:167], v[172:175], v[120:123]
	v_mfma_f32_16x16x32_bf16 v[108:111], v[156:159], v[180:183], v[108:111]
	v_mfma_f32_16x16x32_bf16 v[104:107], v[164:167], v[180:183], v[104:107]
	v_mfma_f32_16x16x32_bf16 v[92:95], v[156:159], v[188:191], v[92:95]
	v_mfma_f32_16x16x32_bf16 v[88:91], v[164:167], v[188:191], v[88:91]
	v_mfma_f32_16x16x32_bf16 v[76:79], v[156:159], v[196:199], v[76:79]
	v_mfma_f32_16x16x32_bf16 v[72:75], v[164:167], v[196:199], v[72:75]
	s_barrier
	s_add_i32 s58, s47, s31
	s_add_u32 s80, s26, s100
	s_addc_u32 s81, s27, s101
	s_mov_b32 m0, s58
	ds_read_b128 v[200:203], v150
	ds_read_b128 v[204:207], v150 offset:1024
	ds_read_b128 v[208:211], v150 offset:2048
	ds_read_b128 v[212:215], v150 offset:3072
	global_load_lds_dwordx4 v132, s[26:27]
	s_add_i32 m0, s58, 0x2000
	s_nop 0
	global_load_lds_dwordx4 v128, s[26:27]
	s_waitcnt vmcnt(10)
	s_barrier
	s_waitcnt lgkmcnt(0)
	s_waitcnt lgkmcnt(0)
	v_mfma_f32_16x16x32_bf16 v[116:119], v[200:203], v[168:171], 0
	v_mfma_f32_16x16x32_bf16 v[112:115], v[208:211], v[168:171], 0
	v_mfma_f32_16x16x32_bf16 v[100:103], v[200:203], v[176:179], 0
	v_mfma_f32_16x16x32_bf16 v[96:99], v[208:211], v[176:179], 0
	v_mfma_f32_16x16x32_bf16 v[84:87], v[200:203], v[184:187], 0
	v_mfma_f32_16x16x32_bf16 v[80:83], v[208:211], v[184:187], 0
	v_mfma_f32_16x16x32_bf16 v[68:71], v[200:203], v[192:195], 0
	v_mfma_f32_16x16x32_bf16 v[64:67], v[208:211], v[192:195], 0
	v_mfma_f32_16x16x32_bf16 v[116:119], v[204:207], v[172:175], v[116:119]
	v_mfma_f32_16x16x32_bf16 v[112:115], v[212:215], v[172:175], v[112:115]
	v_mfma_f32_16x16x32_bf16 v[100:103], v[204:207], v[180:183], v[100:103]
	v_mfma_f32_16x16x32_bf16 v[96:99], v[212:215], v[180:183], v[96:99]
	v_mfma_f32_16x16x32_bf16 v[84:87], v[204:207], v[188:191], v[84:87]
	v_mfma_f32_16x16x32_bf16 v[80:83], v[212:215], v[188:191], v[80:83]
	v_mfma_f32_16x16x32_bf16 v[68:71], v[204:207], v[196:199], v[68:71]
	v_mfma_f32_16x16x32_bf16 v[64:67], v[212:215], v[196:199], v[64:67]
	s_mov_b32 m0, s19
	s_add_u32 s82, s28, s100
	s_addc_u32 s83, s29, s101
	s_barrier
	ds_read_b128 v[168:171], v149 offset:16384
	ds_read_b128 v[172:175], v149 offset:17408
	ds_read_b128 v[176:179], v149 offset:18432
	ds_read_b128 v[180:183], v149 offset:19456
	ds_read_b128 v[184:187], v149 offset:20480
	ds_read_b128 v[188:191], v149 offset:21504
	ds_read_b128 v[192:195], v149 offset:22528
	ds_read_b128 v[196:199], v149 offset:23552
	global_load_lds_dwordx4 v134, s[28:29]
	s_mov_b32 m0, s42
	s_nop 0
	global_load_lds_dwordx4 v130, s[28:29]
	s_barrier
	s_waitcnt lgkmcnt(0)
	s_waitcnt lgkmcnt(0)
	v_mfma_f32_16x16x32_bf16 v[60:63], v[152:155], v[168:171], 0
	v_mfma_f32_16x16x32_bf16 v[56:59], v[160:163], v[168:171], 0
	v_mfma_f32_16x16x32_bf16 v[44:47], v[152:155], v[176:179], 0
	v_mfma_f32_16x16x32_bf16 v[40:43], v[160:163], v[176:179], 0
	v_mfma_f32_16x16x32_bf16 v[28:31], v[152:155], v[184:187], 0
	v_mfma_f32_16x16x32_bf16 v[24:27], v[160:163], v[184:187], 0
	v_mfma_f32_16x16x32_bf16 v[12:15], v[152:155], v[192:195], 0
	v_mfma_f32_16x16x32_bf16 v[8:11], v[160:163], v[192:195], 0
	v_mfma_f32_16x16x32_bf16 v[60:63], v[156:159], v[172:175], v[60:63]
	v_mfma_f32_16x16x32_bf16 v[56:59], v[164:167], v[172:175], v[56:59]
	v_mfma_f32_16x16x32_bf16 v[44:47], v[156:159], v[180:183], v[44:47]
	v_mfma_f32_16x16x32_bf16 v[40:43], v[164:167], v[180:183], v[40:43]
	v_mfma_f32_16x16x32_bf16 v[28:31], v[156:159], v[188:191], v[28:31]
	v_mfma_f32_16x16x32_bf16 v[24:27], v[164:167], v[188:191], v[24:27]
	v_mfma_f32_16x16x32_bf16 v[12:15], v[156:159], v[196:199], v[12:15]
	v_mfma_f32_16x16x32_bf16 v[8:11], v[164:167], v[196:199], v[8:11]
	s_barrier
	s_add_u32 s58, s26, 0x40000
	s_addc_u32 s59, s27, 0
	s_add_i32 s60, s48, s31
	s_mov_b32 m0, s60
	s_nop 0
	global_load_lds_dwordx4 v132, s[58:59]
	s_add_i32 m0, s60, 0x2000
	s_nop 0
	global_load_lds_dwordx4 v128, s[58:59]
	s_waitcnt vmcnt(8)
	s_barrier
	v_mfma_f32_16x16x32_bf16 v[52:55], v[200:203], v[168:171], 0
	v_mfma_f32_16x16x32_bf16 v[48:51], v[208:211], v[168:171], 0
	v_mfma_f32_16x16x32_bf16 v[36:39], v[200:203], v[176:179], 0
	v_mfma_f32_16x16x32_bf16 v[32:35], v[208:211], v[176:179], 0
	v_mfma_f32_16x16x32_bf16 v[20:23], v[200:203], v[184:187], 0
	v_mfma_f32_16x16x32_bf16 v[16:19], v[208:211], v[184:187], 0
	v_mfma_f32_16x16x32_bf16 v[4:7], v[200:203], v[192:195], 0
	v_mfma_f32_16x16x32_bf16 v[0:3], v[208:211], v[192:195], 0
	v_mfma_f32_16x16x32_bf16 v[52:55], v[204:207], v[172:175], v[52:55]
	v_mfma_f32_16x16x32_bf16 v[48:51], v[212:215], v[172:175], v[48:51]
	v_mfma_f32_16x16x32_bf16 v[36:39], v[204:207], v[180:183], v[36:39]
	v_mfma_f32_16x16x32_bf16 v[32:35], v[212:215], v[180:183], v[32:35]
	v_mfma_f32_16x16x32_bf16 v[20:23], v[204:207], v[188:191], v[20:23]
	v_mfma_f32_16x16x32_bf16 v[16:19], v[212:215], v[188:191], v[16:19]
	v_mfma_f32_16x16x32_bf16 v[4:7], v[204:207], v[196:199], v[4:7]
	v_mfma_f32_16x16x32_bf16 v[0:3], v[212:215], v[196:199], v[0:3]
	s_add_i32 s58, 0, 0x18000
	v_add_u32_e32 v151, s58, v145
	s_barrier
	s_branch .Lg893_mid
.LBB0_893:
	ds_read_b128 v[152:155], v148
	ds_read_b128 v[156:159], v148 offset:1024
	ds_read_b128 v[160:163], v148 offset:2048
	ds_read_b128 v[164:167], v148 offset:3072
	s_add_u32 s26, s20, 0xfffc0000
	s_addc_u32 s27, s21, -1
	s_add_u32 s26, s26, s98
	s_addc_u32 s27, s27, s99
	s_sub_i32 s89, 0, s98
	s_not_b32 s90, s99
	s_cmp_eq_u32 s57, 12
	s_cselect_b32 s29, s13, s27
	s_cselect_b32 s28, s53, s26
	s_cselect_b32 s27, s11, s56
	s_cselect_b32 s26, s54, s55
	s_cselect_b32 s100, s89, s98
	s_cselect_b32 s101, s90, s99
	s_add_i32 m0, s19, 0xc000
	ds_read_b128 v[168:171], v149
	ds_read_b128 v[172:175], v149 offset:1024
	ds_read_b128 v[176:179], v149 offset:2048
	ds_read_b128 v[180:183], v149 offset:3072
	ds_read_b128 v[184:187], v149 offset:4096
	ds_read_b128 v[188:191], v149 offset:5120
	ds_read_b128 v[192:195], v149 offset:6144
	ds_read_b128 v[196:199], v149 offset:7168
	global_load_lds_dwordx4 v136, s[20:21]
	s_add_i32 m0, s19, 0xe000
	s_nop 0
	global_load_lds_dwordx4 v138, s[20:21]
	s_waitcnt lgkmcnt(8)
	s_barrier
	s_waitcnt lgkmcnt(0)
	s_waitcnt lgkmcnt(0)
	v_mfma_f32_16x16x32_bf16 v[124:127], v[152:155], v[168:171], v[124:127]
	v_mfma_f32_16x16x32_bf16 v[120:123], v[160:163], v[168:171], v[120:123]
	v_mfma_f32_16x16x32_bf16 v[108:111], v[152:155], v[176:179], v[108:111]
	v_mfma_f32_16x16x32_bf16 v[104:107], v[160:163], v[176:179], v[104:107]
	v_mfma_f32_16x16x32_bf16 v[92:95], v[152:155], v[184:187], v[92:95]
	v_mfma_f32_16x16x32_bf16 v[88:91], v[160:163], v[184:187], v[88:91]
	v_mfma_f32_16x16x32_bf16 v[76:79], v[152:155], v[192:195], v[76:79]
	v_mfma_f32_16x16x32_bf16 v[72:75], v[160:163], v[192:195], v[72:75]
	v_mfma_f32_16x16x32_bf16 v[124:127], v[156:159], v[172:175], v[124:127]
	v_mfma_f32_16x16x32_bf16 v[120:123], v[164:167], v[172:175], v[120:123]
	v_mfma_f32_16x16x32_bf16 v[108:111], v[156:159], v[180:183], v[108:111]
	v_mfma_f32_16x16x32_bf16 v[104:107], v[164:167], v[180:183], v[104:107]
	v_mfma_f32_16x16x32_bf16 v[92:95], v[156:159], v[188:191], v[92:95]
	v_mfma_f32_16x16x32_bf16 v[88:91], v[164:167], v[188:191], v[88:91]
	v_mfma_f32_16x16x32_bf16 v[76:79], v[156:159], v[196:199], v[76:79]
	v_mfma_f32_16x16x32_bf16 v[72:75], v[164:167], v[196:199], v[72:75]
	s_barrier
	s_add_i32 s58, s47, s31
	s_add_u32 s80, s26, s100
	s_addc_u32 s81, s27, s101
	s_mov_b32 m0, s58
	ds_read_b128 v[200:203], v150
	ds_read_b128 v[204:207], v150 offset:1024
	ds_read_b128 v[208:211], v150 offset:2048
	ds_read_b128 v[212:215], v150 offset:3072
	global_load_lds_dwordx4 v132, s[26:27]
	s_add_i32 m0, s58, 0x2000
	s_nop 0
	global_load_lds_dwordx4 v128, s[26:27]
	s_waitcnt vmcnt(10)
	s_barrier
	s_waitcnt lgkmcnt(0)
	s_waitcnt lgkmcnt(0)
	v_mfma_f32_16x16x32_bf16 v[116:119], v[200:203], v[168:171], v[116:119]
	v_mfma_f32_16x16x32_bf16 v[112:115], v[208:211], v[168:171], v[112:115]
	v_mfma_f32_16x16x32_bf16 v[100:103], v[200:203], v[176:179], v[100:103]
	v_mfma_f32_16x16x32_bf16 v[96:99], v[208:211], v[176:179], v[96:99]
	v_mfma_f32_16x16x32_bf16 v[84:87], v[200:203], v[184:187], v[84:87]
	v_mfma_f32_16x16x32_bf16 v[80:83], v[208:211], v[184:187], v[80:83]
	v_mfma_f32_16x16x32_bf16 v[68:71], v[200:203], v[192:195], v[68:71]
	v_mfma_f32_16x16x32_bf16 v[64:67], v[208:211], v[192:195], v[64:67]
	v_mfma_f32_16x16x32_bf16 v[116:119], v[204:207], v[172:175], v[116:119]
	v_mfma_f32_16x16x32_bf16 v[112:115], v[212:215], v[172:175], v[112:115]
	v_mfma_f32_16x16x32_bf16 v[100:103], v[204:207], v[180:183], v[100:103]
	v_mfma_f32_16x16x32_bf16 v[96:99], v[212:215], v[180:183], v[96:99]
	v_mfma_f32_16x16x32_bf16 v[84:87], v[204:207], v[188:191], v[84:87]
	v_mfma_f32_16x16x32_bf16 v[80:83], v[212:215], v[188:191], v[80:83]
	v_mfma_f32_16x16x32_bf16 v[68:71], v[204:207], v[196:199], v[68:71]
	v_mfma_f32_16x16x32_bf16 v[64:67], v[212:215], v[196:199], v[64:67]
	s_mov_b32 m0, s19
	s_add_u32 s82, s28, s100
	s_addc_u32 s83, s29, s101
	s_barrier
	ds_read_b128 v[168:171], v149 offset:16384
	ds_read_b128 v[172:175], v149 offset:17408
	ds_read_b128 v[176:179], v149 offset:18432
	ds_read_b128 v[180:183], v149 offset:19456
	ds_read_b128 v[184:187], v149 offset:20480
	ds_read_b128 v[188:191], v149 offset:21504
	ds_read_b128 v[192:195], v149 offset:22528
	ds_read_b128 v[196:199], v149 offset:23552
	global_load_lds_dwordx4 v134, s[28:29]
	s_mov_b32 m0, s42
	s_nop 0
	global_load_lds_dwordx4 v130, s[28:29]
	s_barrier
	s_waitcnt lgkmcnt(0)
	s_waitcnt lgkmcnt(0)
	v_mfma_f32_16x16x32_bf16 v[60:63], v[152:155], v[168:171], v[60:63]
	v_mfma_f32_16x16x32_bf16 v[56:59], v[160:163], v[168:171], v[56:59]
	v_mfma_f32_16x16x32_bf16 v[44:47], v[152:155], v[176:179], v[44:47]
	v_mfma_f32_16x16x32_bf16 v[40:43], v[160:163], v[176:179], v[40:43]
	v_mfma_f32_16x16x32_bf16 v[28:31], v[152:155], v[184:187], v[28:31]
	v_mfma_f32_16x16x32_bf16 v[24:27], v[160:163], v[184:187], v[24:27]
	v_mfma_f32_16x16x32_bf16 v[12:15], v[152:155], v[192:195], v[12:15]
	v_mfma_f32_16x16x32_bf16 v[8:11], v[160:163], v[192:195], v[8:11]
	v_mfma_f32_16x16x32_bf16 v[60:63], v[156:159], v[172:175], v[60:63]
	v_mfma_f32_16x16x32_bf16 v[56:59], v[164:167], v[172:175], v[56:59]
	v_mfma_f32_16x16x32_bf16 v[44:47], v[156:159], v[180:183], v[44:47]
	v_mfma_f32_16x16x32_bf16 v[40:43], v[164:167], v[180:183], v[40:43]
	v_mfma_f32_16x16x32_bf16 v[28:31], v[156:159], v[188:191], v[28:31]
	v_mfma_f32_16x16x32_bf16 v[24:27], v[164:167], v[188:191], v[24:27]
	v_mfma_f32_16x16x32_bf16 v[12:15], v[156:159], v[196:199], v[12:15]
	v_mfma_f32_16x16x32_bf16 v[8:11], v[164:167], v[196:199], v[8:11]
	s_barrier
	s_add_u32 s58, s26, 0x40000
	s_addc_u32 s59, s27, 0
	s_add_i32 s60, s48, s31
	s_mov_b32 m0, s60
	s_nop 0
	global_load_lds_dwordx4 v132, s[58:59]
	s_add_i32 m0, s60, 0x2000
	s_nop 0
	global_load_lds_dwordx4 v128, s[58:59]
	s_waitcnt vmcnt(8)
	s_barrier
	v_mfma_f32_16x16x32_bf16 v[52:55], v[200:203], v[168:171], v[52:55]
	v_mfma_f32_16x16x32_bf16 v[48:51], v[208:211], v[168:171], v[48:51]
	v_mfma_f32_16x16x32_bf16 v[36:39], v[200:203], v[176:179], v[36:39]
	v_mfma_f32_16x16x32_bf16 v[32:35], v[208:211], v[176:179], v[32:35]
	v_mfma_f32_16x16x32_bf16 v[20:23], v[200:203], v[184:187], v[20:23]
	v_mfma_f32_16x16x32_bf16 v[16:19], v[208:211], v[184:187], v[16:19]
	v_mfma_f32_16x16x32_bf16 v[4:7], v[200:203], v[192:195], v[4:7]
	v_mfma_f32_16x16x32_bf16 v[0:3], v[208:211], v[192:195], v[0:3]
	v_mfma_f32_16x16x32_bf16 v[52:55], v[204:207], v[172:175], v[52:55]
	v_mfma_f32_16x16x32_bf16 v[48:51], v[212:215], v[172:175], v[48:51]
	v_mfma_f32_16x16x32_bf16 v[36:39], v[204:207], v[180:183], v[36:39]
	v_mfma_f32_16x16x32_bf16 v[32:35], v[212:215], v[180:183], v[32:35]
	v_mfma_f32_16x16x32_bf16 v[20:23], v[204:207], v[188:191], v[20:23]
	v_mfma_f32_16x16x32_bf16 v[16:19], v[212:215], v[188:191], v[16:19]
	v_mfma_f32_16x16x32_bf16 v[4:7], v[204:207], v[196:199], v[4:7]
	v_mfma_f32_16x16x32_bf16 v[0:3], v[212:215], v[196:199], v[0:3]
	s_add_i32 s58, 0, 0x18000
	v_add_u32_e32 v151, s58, v145
	s_barrier
.Lg893_mid:
	ds_read_b128 v[152:155], v151
	ds_read_b128 v[156:159], v151 offset:1024
	ds_read_b128 v[160:163], v151 offset:2048
	ds_read_b128 v[164:167], v151 offset:3072
	s_add_u32 s28, s28, 0x40000
	s_addc_u32 s29, s29, 0
	s_mov_b32 m0, s43
	ds_read_b128 v[168:171], v149 offset:32768
	ds_read_b128 v[172:175], v149 offset:33792
	ds_read_b128 v[176:179], v149 offset:34816
	ds_read_b128 v[180:183], v149 offset:35840
	ds_read_b128 v[184:187], v149 offset:36864
	ds_read_b128 v[188:191], v149 offset:37888
	ds_read_b128 v[192:195], v149 offset:38912
	ds_read_b128 v[196:199], v149 offset:39936
	global_load_lds_dwordx4 v134, s[28:29]
	s_mov_b32 m0, s44
	s_nop 0
	global_load_lds_dwordx4 v130, s[28:29]
	s_waitcnt lgkmcnt(8)
	s_barrier
	s_waitcnt lgkmcnt(0)
	s_waitcnt lgkmcnt(0)
	v_mfma_f32_16x16x32_bf16 v[124:127], v[152:155], v[168:171], v[124:127]
	v_mfma_f32_16x16x32_bf16 v[120:123], v[160:163], v[168:171], v[120:123]
	v_mfma_f32_16x16x32_bf16 v[108:111], v[152:155], v[176:179], v[108:111]
	v_mfma_f32_16x16x32_bf16 v[104:107], v[160:163], v[176:179], v[104:107]
	v_mfma_f32_16x16x32_bf16 v[92:95], v[152:155], v[184:187], v[92:95]
	v_mfma_f32_16x16x32_bf16 v[88:91], v[160:163], v[184:187], v[88:91]
	v_mfma_f32_16x16x32_bf16 v[76:79], v[152:155], v[192:195], v[76:79]
	v_mfma_f32_16x16x32_bf16 v[72:75], v[160:163], v[192:195], v[72:75]
	v_mfma_f32_16x16x32_bf16 v[124:127], v[156:159], v[172:175], v[124:127]
	v_mfma_f32_16x16x32_bf16 v[120:123], v[164:167], v[172:175], v[120:123]
	v_mfma_f32_16x16x32_bf16 v[108:111], v[156:159], v[180:183], v[108:111]
	v_mfma_f32_16x16x32_bf16 v[104:107], v[164:167], v[180:183], v[104:107]
	v_mfma_f32_16x16x32_bf16 v[92:95], v[156:159], v[188:191], v[92:95]
	v_mfma_f32_16x16x32_bf16 v[88:91], v[164:167], v[188:191], v[88:91]
	v_mfma_f32_16x16x32_bf16 v[76:79], v[156:159], v[196:199], v[76:79]
	v_mfma_f32_16x16x32_bf16 v[72:75], v[164:167], v[196:199], v[72:75]
	s_barrier
	s_add_i32 s28, 0, 0x1c000
	s_add_i32 s29, s58, s31
	v_add_u32_e32 v151, s28, v145
	s_mov_b32 m0, s29
	ds_read_b128 v[200:203], v151
	ds_read_b128 v[204:207], v151 offset:1024
	ds_read_b128 v[208:211], v151 offset:2048
	ds_read_b128 v[212:215], v151 offset:3072
	global_load_lds_dwordx4 v132, s[80:81]
	s_add_i32 m0, s29, 0x2000
	s_nop 0
	global_load_lds_dwordx4 v128, s[80:81]
	s_waitcnt vmcnt(10)
	s_barrier
	s_waitcnt lgkmcnt(0)
	s_waitcnt lgkmcnt(0)
	v_mfma_f32_16x16x32_bf16 v[116:119], v[200:203], v[168:171], v[116:119]
	v_mfma_f32_16x16x32_bf16 v[112:115], v[208:211], v[168:171], v[112:115]
	v_mfma_f32_16x16x32_bf16 v[100:103], v[200:203], v[176:179], v[100:103]
	v_mfma_f32_16x16x32_bf16 v[96:99], v[208:211], v[176:179], v[96:99]
	v_mfma_f32_16x16x32_bf16 v[84:87], v[200:203], v[184:187], v[84:87]
	v_mfma_f32_16x16x32_bf16 v[80:83], v[208:211], v[184:187], v[80:83]
	v_mfma_f32_16x16x32_bf16 v[68:71], v[200:203], v[192:195], v[68:71]
	v_mfma_f32_16x16x32_bf16 v[64:67], v[208:211], v[192:195], v[64:67]
	v_mfma_f32_16x16x32_bf16 v[116:119], v[204:207], v[172:175], v[116:119]
	v_mfma_f32_16x16x32_bf16 v[112:115], v[212:215], v[172:175], v[112:115]
	v_mfma_f32_16x16x32_bf16 v[100:103], v[204:207], v[180:183], v[100:103]
	v_mfma_f32_16x16x32_bf16 v[96:99], v[212:215], v[180:183], v[96:99]
	v_mfma_f32_16x16x32_bf16 v[84:87], v[204:207], v[188:191], v[84:87]
	v_mfma_f32_16x16x32_bf16 v[80:83], v[212:215], v[188:191], v[80:83]
	v_mfma_f32_16x16x32_bf16 v[68:71], v[204:207], v[196:199], v[68:71]
	v_mfma_f32_16x16x32_bf16 v[64:67], v[212:215], v[196:199], v[64:67]
	s_mov_b32 m0, s45
	s_barrier
	ds_read_b128 v[168:171], v149 offset:49152
	ds_read_b128 v[172:175], v149 offset:50176
	ds_read_b128 v[176:179], v149 offset:51200
	ds_read_b128 v[180:183], v149 offset:52224
	ds_read_b128 v[184:187], v149 offset:53248
	ds_read_b128 v[188:191], v149 offset:54272
	ds_read_b128 v[192:195], v149 offset:55296
	ds_read_b128 v[196:199], v149 offset:56320
	global_load_lds_dwordx4 v134, s[82:83]
	s_mov_b32 m0, s46
	s_nop 0
	global_load_lds_dwordx4 v130, s[82:83]
	s_barrier
	s_waitcnt lgkmcnt(0)
	s_waitcnt lgkmcnt(0)
	v_mfma_f32_16x16x32_bf16 v[60:63], v[152:155], v[168:171], v[60:63]
	v_mfma_f32_16x16x32_bf16 v[56:59], v[160:163], v[168:171], v[56:59]
	v_mfma_f32_16x16x32_bf16 v[44:47], v[152:155], v[176:179], v[44:47]
	v_mfma_f32_16x16x32_bf16 v[40:43], v[160:163], v[176:179], v[40:43]
	v_mfma_f32_16x16x32_bf16 v[28:31], v[152:155], v[184:187], v[28:31]
	v_mfma_f32_16x16x32_bf16 v[24:27], v[160:163], v[184:187], v[24:27]
	v_mfma_f32_16x16x32_bf16 v[12:15], v[152:155], v[192:195], v[12:15]
	v_mfma_f32_16x16x32_bf16 v[8:11], v[160:163], v[192:195], v[8:11]
	v_mfma_f32_16x16x32_bf16 v[60:63], v[156:159], v[172:175], v[60:63]
	v_mfma_f32_16x16x32_bf16 v[56:59], v[164:167], v[172:175], v[56:59]
	v_mfma_f32_16x16x32_bf16 v[44:47], v[156:159], v[180:183], v[44:47]
	v_mfma_f32_16x16x32_bf16 v[40:43], v[164:167], v[180:183], v[40:43]
	v_mfma_f32_16x16x32_bf16 v[28:31], v[156:159], v[188:191], v[28:31]
	v_mfma_f32_16x16x32_bf16 v[24:27], v[164:167], v[188:191], v[24:27]
	v_mfma_f32_16x16x32_bf16 v[12:15], v[156:159], v[196:199], v[12:15]
	v_mfma_f32_16x16x32_bf16 v[8:11], v[164:167], v[196:199], v[8:11]
	s_barrier
	s_add_u32 s26, s26, 0x40000
	s_addc_u32 s27, s27, 0
	s_add_u32 s26, s26, s100
	s_addc_u32 s27, s27, s101
	s_add_i32 s28, s28, s31
	s_mov_b32 m0, s28
	s_nop 0
	global_load_lds_dwordx4 v132, s[26:27]
	s_add_i32 m0, s28, 0x2000
	s_nop 0
	global_load_lds_dwordx4 v128, s[26:27]
	s_waitcnt vmcnt(8)
	s_barrier
	v_mfma_f32_16x16x32_bf16 v[52:55], v[200:203], v[168:171], v[52:55]
	v_mfma_f32_16x16x32_bf16 v[48:51], v[208:211], v[168:171], v[48:51]
	v_mfma_f32_16x16x32_bf16 v[36:39], v[200:203], v[176:179], v[36:39]
	v_mfma_f32_16x16x32_bf16 v[32:35], v[208:211], v[176:179], v[32:35]
	v_mfma_f32_16x16x32_bf16 v[20:23], v[200:203], v[184:187], v[20:23]
	v_mfma_f32_16x16x32_bf16 v[16:19], v[208:211], v[184:187], v[16:19]
	v_mfma_f32_16x16x32_bf16 v[4:7], v[200:203], v[192:195], v[4:7]
	v_mfma_f32_16x16x32_bf16 v[0:3], v[208:211], v[192:195], v[0:3]
	v_mfma_f32_16x16x32_bf16 v[52:55], v[204:207], v[172:175], v[52:55]
	v_mfma_f32_16x16x32_bf16 v[48:51], v[212:215], v[172:175], v[48:51]
	v_mfma_f32_16x16x32_bf16 v[36:39], v[204:207], v[180:183], v[36:39]
	v_mfma_f32_16x16x32_bf16 v[32:35], v[212:215], v[180:183], v[32:35]
	v_mfma_f32_16x16x32_bf16 v[20:23], v[204:207], v[188:191], v[20:23]
	v_mfma_f32_16x16x32_bf16 v[16:19], v[212:215], v[188:191], v[16:19]
	v_mfma_f32_16x16x32_bf16 v[4:7], v[204:207], v[196:199], v[4:7]
	v_mfma_f32_16x16x32_bf16 v[0:3], v[212:215], v[196:199], v[0:3]
	s_add_i32 s57, s57, 2
	s_lshl_b32 s88, s98, 1
	s_add_u32 s20, s20, s88
	s_addc_u32 s21, s21, s99
	s_add_u32 s55, s55, s88
	s_addc_u32 s56, s56, s99
	s_cmp_gt_u32 s57, 13
	s_barrier
	s_cbranch_scc0 .LBB0_893
	s_setprio 0
	s_cmpk_gt_u32 s30, 0xff
	s_cbranch_scc1 .Lg893_nox
	s_barrier
	s_setprio 1

	.amdhsa_kernel _Z9hymba_fwd6Params
		.amdhsa_group_segment_fixed_size 0
		.amdhsa_private_segment_fixed_size 0
		.amdhsa_kernarg_size 432
		.amdhsa_user_sgpr_count 2
		.amdhsa_user_sgpr_dispatch_ptr 0
		.amdhsa_user_sgpr_queue_ptr 0
		.amdhsa_user_sgpr_kernarg_segment_ptr 1
		.amdhsa_user_sgpr_dispatch_id 0
		.amdhsa_user_sgpr_kernarg_preload_length 0
		.amdhsa_user_sgpr_kernarg_preload_offset 0
		.amdhsa_user_sgpr_private_segment_size 0
		.amdhsa_uses_dynamic_stack 0
		.amdhsa_enable_private_segment 0
		.amdhsa_system_sgpr_workgroup_id_x 1
		.amdhsa_system_sgpr_workgroup_id_y 0
		.amdhsa_system_sgpr_workgroup_id_z 0
		.amdhsa_system_sgpr_workgroup_info 0
		.amdhsa_system_vgpr_workitem_id 2
		.amdhsa_next_free_vgpr 248
		.amdhsa_next_free_sgpr 102
		.amdhsa_accum_offset 248
		.amdhsa_reserve_vcc 1
		.amdhsa_float_round_mode_32 0
		.amdhsa_float_round_mode_16_64 0
		.amdhsa_float_denorm_mode_32 3
		.amdhsa_float_denorm_mode_16_64 3
		.amdhsa_dx10_clamp 1
		.amdhsa_ieee_mode 1
		.amdhsa_fp16_overflow 0
		.amdhsa_tg_split 0
		.amdhsa_exception_fp_ieee_invalid_op 0
		.amdhsa_exception_fp_denorm_src 0
		.amdhsa_exception_fp_ieee_div_zero 0
		.amdhsa_exception_fp_ieee_overflow 0
		.amdhsa_exception_fp_ieee_underflow 0
		.amdhsa_exception_fp_ieee_inexact 0
		.amdhsa_exception_int_div_zero 0
	.end_amdhsa_kernel

amdhsa.kernels:
  - .agpr_count:     0
    .args:
      - .offset:         0
        .size:           176
        .value_kind:     by_value
      - .offset:         176
        .size:           4
        .value_kind:     hidden_block_count_x
      - .offset:         180
        .size:           4
        .value_kind:     hidden_block_count_y
      - .offset:         184
        .size:           4
        .value_kind:     hidden_block_count_z
      - .offset:         188
        .size:           2
        .value_kind:     hidden_group_size_x
      - .offset:         190
        .size:           2
        .value_kind:     hidden_group_size_y
      - .offset:         192
        .size:           2
        .value_kind:     hidden_group_size_z
      - .offset:         194
        .size:           2
        .value_kind:     hidden_remainder_x
      - .offset:         196
        .size:           2
        .value_kind:     hidden_remainder_y
      - .offset:         198
        .size:           2
        .value_kind:     hidden_remainder_z
      - .offset:         216
        .size:           8
        .value_kind:     hidden_global_offset_x
      - .offset:         224
        .size:           8
        .value_kind:     hidden_global_offset_y
      - .offset:         232
        .size:           8
        .value_kind:     hidden_global_offset_z
      - .offset:         240
        .size:           2
        .value_kind:     hidden_grid_dims
      - .offset:         264
        .size:           8
        .value_kind:     hidden_multigrid_sync_arg
      - .offset:         296
        .size:           4
        .value_kind:     hidden_dynamic_lds_size
    .group_segment_fixed_size: 0
    .kernarg_segment_align: 8
    .kernarg_segment_size: 432
    .language:       OpenCL C
    .language_version:
      - 2
      - 0
    .max_flat_workgroup_size: 512
    .name:           _Z9hymba_fwd6Params
    .private_segment_fixed_size: 0
    .sgpr_count:     108
    .sgpr_spill_count: 0
    .symbol:         _Z9hymba_fwd6Params.kd
    .uniform_work_group_size: 1
    .uses_dynamic_stack: false
    .vgpr_count:     248
    .vgpr_spill_count: 0
    .wavefront_size: 64
